# v60 + softmax exps in place, row-sum via v_pk_add_f32 (two partial sums), l update as one fma
# speedup vs baseline: 1.0048x; 1.0047x over previous
; __device__ __forceinline__ bool softmax_pp(f32x16& p0, f32x16& p1, float& m_reg, float& l_reg, f32x16& negm, float& alpha, float& m_run, float dq, float nslope,
;                                            bf16x8& pa0, bf16x8& pa1, bf16x8& pa2, bf16x8& pa3) {
;     ...
;   for (int r = 0; r < 16; ++r) { p0[r] = __builtin_amdgcn_exp2f(p0[r]); p1[r] = __builtin_amdgcn_exp2f(p1[r]); }
;   float ps = 0;
; #pragma unroll
;   for (int r = 0; r < 16; ++r) ps += p0[r];
; #pragma unroll
;   for (int r = 0; r < 16; ++r) ps += p1[r];
;   { auto rr = __builtin_amdgcn_permlane32_swap(__float_as_uint(ps), __float_as_uint(ps), false, false);
;     ps = __uint_as_float(rr[0]) + __uint_as_float(rr[1]); }
;   l_reg = l_reg * alpha + ps;
;     ...
;   PK4(p0, 0, pa0); PK4(p0, 8, pa1); PK4(p1, 0, pa2); PK4(p1, 8, pa3);
.LBB0_369:
	v_max_f32_e32 v172, v172, v15
	v_exp_f32_e32 v98, v98
	v_exp_f32_e32 v99, v99
	v_exp_f32_e32 v100, v100
	v_exp_f32_e32 v101, v101
	v_exp_f32_e32 v102, v102
	v_exp_f32_e32 v103, v103
	v_pk_add_f32 v[14:15], v[98:99], v[100:101]
	v_exp_f32_e32 v104, v104
	v_exp_f32_e32 v105, v105
	v_pk_add_f32 v[14:15], v[14:15], v[102:103]
	v_exp_f32_e32 v106, v106
	v_exp_f32_e32 v107, v107
	v_pk_add_f32 v[14:15], v[14:15], v[104:105]
	v_exp_f32_e32 v108, v108
	v_exp_f32_e32 v109, v109
	v_pk_add_f32 v[14:15], v[14:15], v[106:107]
	v_exp_f32_e32 v110, v110
	v_exp_f32_e32 v111, v111
	v_pk_add_f32 v[14:15], v[14:15], v[108:109]
	v_exp_f32_e32 v112, v112
	v_exp_f32_e32 v113, v113
	v_pk_add_f32 v[14:15], v[14:15], v[110:111]
	v_exp_f32_e32 v114, v114
	v_exp_f32_e32 v115, v115
	v_pk_add_f32 v[14:15], v[14:15], v[112:113]
	v_exp_f32_e32 v116, v116
	v_exp_f32_e32 v117, v117
	v_pk_add_f32 v[14:15], v[14:15], v[114:115]
	v_exp_f32_e32 v118, v118
	v_exp_f32_e32 v119, v119
	v_pk_add_f32 v[14:15], v[14:15], v[116:117]
	v_exp_f32_e32 v120, v120
	v_exp_f32_e32 v121, v121
	v_pk_add_f32 v[14:15], v[14:15], v[118:119]
	v_exp_f32_e32 v122, v122
	v_exp_f32_e32 v123, v123
	v_pk_add_f32 v[14:15], v[14:15], v[120:121]
	v_exp_f32_e32 v124, v124
	v_exp_f32_e32 v125, v125
	v_pk_add_f32 v[14:15], v[14:15], v[122:123]
	v_exp_f32_e32 v126, v126
	v_exp_f32_e32 v127, v127
	v_pk_add_f32 v[14:15], v[14:15], v[124:125]
	v_exp_f32_e32 v128, v128
	v_exp_f32_e32 v129, v129
	v_pk_add_f32 v[14:15], v[14:15], v[126:127]
	v_cvt_pk_bf16_f32 v2, v98, v99
	v_cvt_pk_bf16_f32 v3, v100, v101
	v_pk_add_f32 v[14:15], v[14:15], v[128:129]
	v_cvt_pk_bf16_f32 v4, v102, v103
	v_cvt_pk_bf16_f32 v5, v104, v105
	v_add_f32_e32 v14, v14, v15
	v_cvt_pk_bf16_f32 v6, v106, v107
	v_cvt_pk_bf16_f32 v7, v108, v109
	v_mov_b32_e32 v15, v14
	v_cvt_pk_bf16_f32 v8, v110, v111
	v_cvt_pk_bf16_f32 v9, v112, v113
	v_cvt_pk_bf16_f32 v10, v114, v115
	v_cvt_pk_bf16_f32 v11, v116, v117
	v_cvt_pk_bf16_f32 v12, v118, v119
	v_cvt_pk_bf16_f32 v13, v120, v121
	v_cvt_pk_bf16_f32 v162, v122, v123
	v_cvt_pk_bf16_f32 v163, v124, v125
	v_cvt_pk_bf16_f32 v164, v126, v127
	v_cvt_pk_bf16_f32 v165, v128, v129
	v_permlane32_swap_b32_e32 v14, v15
	v_permlane32_swap_b32_e32 v2, v4
	v_permlane32_swap_b32_e32 v3, v5
	v_permlane32_swap_b32_e32 v6, v8
	v_permlane32_swap_b32_e32 v7, v9
	v_permlane32_swap_b32_e32 v10, v12
	v_permlane32_swap_b32_e32 v11, v13
	v_permlane32_swap_b32_e32 v162, v164
	v_permlane32_swap_b32_e32 v163, v165
	v_add_f32_e32 v14, v14, v15
	v_fma_f32 v80, v80, v0, v14
	s_branch .LBB0_371

; __device__ __forceinline__ bool softmax_pp(f32x16& p0, f32x16& p1, float& m_reg, float& l_reg, f32x16& negm, float& alpha, float& m_run, float dq, float nslope,
;                                            bf16x8& pa0, bf16x8& pa1, bf16x8& pa2, bf16x8& pa3) {
;     ...
;   for (int r = 0; r < 16; ++r) { p0[r] = __builtin_amdgcn_exp2f(p0[r]); p1[r] = __builtin_amdgcn_exp2f(p1[r]); }
;   float ps = 0;
; #pragma unroll
;   for (int r = 0; r < 16; ++r) ps += p0[r];
; #pragma unroll
;   for (int r = 0; r < 16; ++r) ps += p1[r];
;   { auto rr = __builtin_amdgcn_permlane32_swap(__float_as_uint(ps), __float_as_uint(ps), false, false);
;     ps = __uint_as_float(rr[0]) + __uint_as_float(rr[1]); }
;   l_reg = l_reg * alpha + ps;
;     ...
;   PK4(p0, 0, pa0); PK4(p0, 8, pa1); PK4(p1, 0, pa2); PK4(p1, 8, pa3);
.LBB0_384:
	v_max_f32_e32 v172, v172, v15
	v_exp_f32_e32 v98, v98
	v_exp_f32_e32 v99, v99
	v_exp_f32_e32 v100, v100
	v_exp_f32_e32 v101, v101
	v_exp_f32_e32 v102, v102
	v_exp_f32_e32 v103, v103
	v_pk_add_f32 v[14:15], v[98:99], v[100:101]
	v_exp_f32_e32 v104, v104
	v_exp_f32_e32 v105, v105
	v_pk_add_f32 v[14:15], v[14:15], v[102:103]
	v_exp_f32_e32 v106, v106
	v_exp_f32_e32 v107, v107
	v_pk_add_f32 v[14:15], v[14:15], v[104:105]
	v_exp_f32_e32 v108, v108
	v_exp_f32_e32 v109, v109
	v_pk_add_f32 v[14:15], v[14:15], v[106:107]
	v_exp_f32_e32 v110, v110
	v_exp_f32_e32 v111, v111
	v_pk_add_f32 v[14:15], v[14:15], v[108:109]
	v_exp_f32_e32 v112, v112
	v_exp_f32_e32 v113, v113
	v_pk_add_f32 v[14:15], v[14:15], v[110:111]
	v_exp_f32_e32 v114, v114
	v_exp_f32_e32 v115, v115
	v_pk_add_f32 v[14:15], v[14:15], v[112:113]
	v_exp_f32_e32 v116, v116
	v_exp_f32_e32 v117, v117
	v_pk_add_f32 v[14:15], v[14:15], v[114:115]
	v_exp_f32_e32 v118, v118
	v_exp_f32_e32 v119, v119
	v_pk_add_f32 v[14:15], v[14:15], v[116:117]
	v_exp_f32_e32 v120, v120
	v_exp_f32_e32 v121, v121
	v_pk_add_f32 v[14:15], v[14:15], v[118:119]
	v_exp_f32_e32 v122, v122
	v_exp_f32_e32 v123, v123
	v_pk_add_f32 v[14:15], v[14:15], v[120:121]
	v_exp_f32_e32 v124, v124
	v_exp_f32_e32 v125, v125
	v_pk_add_f32 v[14:15], v[14:15], v[122:123]
	v_exp_f32_e32 v126, v126
	v_exp_f32_e32 v127, v127
	v_pk_add_f32 v[14:15], v[14:15], v[124:125]
	v_exp_f32_e32 v128, v128
	v_exp_f32_e32 v129, v129
	v_pk_add_f32 v[14:15], v[14:15], v[126:127]
	v_cvt_pk_bf16_f32 v2, v98, v99
	v_cvt_pk_bf16_f32 v3, v100, v101
	v_pk_add_f32 v[14:15], v[14:15], v[128:129]
	v_cvt_pk_bf16_f32 v4, v102, v103
	v_cvt_pk_bf16_f32 v5, v104, v105
	v_add_f32_e32 v14, v14, v15
	v_cvt_pk_bf16_f32 v6, v106, v107
	v_cvt_pk_bf16_f32 v7, v108, v109
	v_mov_b32_e32 v15, v14
	v_cvt_pk_bf16_f32 v8, v110, v111
	v_cvt_pk_bf16_f32 v9, v112, v113
	v_cvt_pk_bf16_f32 v10, v114, v115
	v_cvt_pk_bf16_f32 v11, v116, v117
	v_cvt_pk_bf16_f32 v12, v118, v119
	v_cvt_pk_bf16_f32 v13, v120, v121
	v_cvt_pk_bf16_f32 v162, v122, v123
	v_cvt_pk_bf16_f32 v163, v124, v125
	v_cvt_pk_bf16_f32 v164, v126, v127
	v_cvt_pk_bf16_f32 v165, v128, v129
	v_permlane32_swap_b32_e32 v14, v15
	v_permlane32_swap_b32_e32 v2, v4
	v_permlane32_swap_b32_e32 v3, v5
	v_permlane32_swap_b32_e32 v6, v8
	v_permlane32_swap_b32_e32 v7, v9
	v_permlane32_swap_b32_e32 v10, v12
	v_permlane32_swap_b32_e32 v11, v13
	v_permlane32_swap_b32_e32 v162, v164
	v_permlane32_swap_b32_e32 v163, v165
	v_add_f32_e32 v14, v14, v15
	v_fma_f32 v80, v80, v0, v14
